# weight (B-tile) stage loads of out-GEMM and attn-out also issued ahead of the closing workgroup barrier (weights converted >=3 grid barriers earlier); rest as residual-prefetch best
# speedup vs baseline: 1.0090x; 1.0000x over previous
; __device__ __forceinline__ void acc_from_xb(AccT& acc, const bf16_t* xb, const Unit& u, int wr, int wc, int fr, int fq) {
;     const unsigned off0 = (unsigned)(u.pm * BM + wr * 64 + fr) * DM + u.pn * BM + wc * 32 + 8 * fq;
; #pragma unroll
;     for (int ai = 0; ai < 2; ++ai)
; #pragma unroll
; template <class Epi, class Sched, bool ALIGN_EPI = false, bool SP2 = false>
; __device__ __forceinline__ void gemm_phase(PG8_LAS unsigned char* lds, const Gemm g, const Sched& S, const Epi& E, const int wid) {
;     const int lane = fresh_lane(), tid = wid * 64 + lane, wr = wid >> 2, wc = wid & 3, fr = lane & 15, fq = lane >> 4;
;     int nt = g.K / BK; asm volatile("" : "+s"(nt));
;     unsigned voffA[2], voffB[2];
; #pragma unroll
;     for (int i = 0; i < 2; ++i) { int R, C; stage_rc(tid * 16 + i * 8192, R, C); const int Rb = Epi::PERM ? ((R & ~31) + perm32(R & 31)) : R;
;         voffA[i] = (unsigned)(R * g.lda + C) * 2u; voffB[i] = (unsigned)(Rb * g.ldb + C) * 2u; }
;     const size_t kstep = (size_t)(BK * 2);
;     const size_t hstepA = (size_t)HALF * g.lda * 2, hstepB = (size_t)HALF * g.ldb * 2;
;     const size_t tstepA = 2 * hstepA, tstepB = 2 * hstepB;
;     const unsigned ldsw = (unsigned)wid * 1024u;
;     const int aoff = lds_byte(wr * 64 + fr, fq * 8), boff = lds_byte(wc * 32 + fr, fq * 8);
;     ...
;     Unit cur, nxt; int ui = 0;
;     if (!S.next(0, cur)) return;
;     f32x4 acc[2][2][4][2];
;     if constexpr (Epi::ACC_INIT) E.init(acc, cur, wr, wc, fr, fq);
;     else {
; #pragma unroll
;     for (int a = 0; a < 2; ++a)
; #pragma unroll
;         for (int b = 0; b < 2; ++b)
; #pragma unroll
;             for (int m = 0; m < 4; ++m)
; #pragma unroll
;                 for (int n = 0; n < 2; ++n) acc[a][b][m][n] = (f32x4){0.f, 0.f, 0.f, 0.f};
;     }
;     bf16x8 At[4][2], B0[2][2], B1[2][2];
;     const char* cA = cur.pn >= g.swap_pn ? (const char*)g.A2 + (size_t)(cur.pn - g.swap_pn) * tstepA : (const char*)g.A + (size_t)cur.pm * tstepA + (g.bd ? (size_t)(cur.pn >> 1) * 512 : 0);
;     const char* cB = cur.pn >= g.swap_pn ? (const char*)g.B2 + (size_t)cur.pm * tstepB : (const char*)g.Bt + (size_t)cur.pn * tstepB;
;     S.a_ready(cur);
;     if constexpr (SP2) {
;         PG8_STAGE(PG8_SB(0, 0), cB, voffB); PG8_STAGE(PG8_SB(0, 1), cB + hstepB, voffB); PG8_STAGE(PG8_SA(0, 0), cA, voffA); PG8_STAGE(PG8_SA(0, 1), cA + hstepA, voffA);
.LBB0_393:
	v_lshlrev_b32_e32 v145, 4, v144
	v_add_u32_e32 v0, s0, v145
	v_ashrrev_i32_e32 v1, 31, v0
	v_lshrrev_b32_e32 v1, 22, v1
	v_add_u32_e32 v1, v0, v1
	v_ashrrev_i32_e32 v149, 10, v1
	v_mul_i32_i24_e32 v1, 0x400, v149
	v_sub_u32_e32 v1, v0, v1
	v_lshrrev_b32_e32 v2, 4, v1
	v_bitop3_b32 v1, v2, v1, 32 bitop3:0x6c
	v_ashrrev_i32_e32 v3, 31, v1
	v_lshrrev_b32_e32 v3, 26, v3
	v_add_u32_e32 v3, v1, v3
	v_lshlrev_b32_e32 v2, 3, v149
	v_ashrrev_i32_e32 v150, 6, v3
	v_and_b32_e32 v3, 0xc0, v3
	v_and_b32_e32 v2, -16, v2
	v_sub_u32_e32 v1, v1, v3
	v_mov_b32_e32 v3, 1
	v_add_u32_e32 v2, v150, v2
	v_ashrrev_i16_sdwa v1, v3, sext(v1) dst_sel:DWORD dst_unused:UNUSED_PAD src0_sel:DWORD src1_sel:BYTE_0
	s_ashr_i32 s4, s7, 3
	v_lshlrev_b32_e32 v4, 5, v149
	v_bfe_i32 v151, v1, 0, 16
	v_lshlrev_b32_e32 v1, 1, v2
	v_lshrrev_b32_e32 v5, 2, v2
	v_and_b32_e32 v6, 3, v150
	s_mov_b32 s7, 0x1fffe0
	v_and_b32_e32 v4, 32, v4
	v_and_b32_e32 v1, 24, v1
	v_and_b32_e32 v5, 4, v5
	v_and_or_b32 v6, v2, s7, v6
	v_or3_b32 v1, v6, v5, v1
	v_add_lshl_u32 v4, v4, v151, 1
	v_add_u32_e32 v0, 0x2000, v0
	v_lshl_add_u32 v64, v1, 11, v4
	v_ashrrev_i32_e32 v1, 31, v0
	v_lshrrev_b32_e32 v1, 22, v1
	v_add_u32_e32 v1, v0, v1
	v_ashrrev_i32_e32 v152, 10, v1
	v_mul_i32_i24_e32 v1, 0x400, v152
	v_sub_u32_e32 v0, v0, v1
	v_lshrrev_b32_e32 v1, 4, v0
	v_bitop3_b32 v0, v1, v0, 32 bitop3:0x6c
	v_lshl_add_u32 v128, v2, 11, v4
	v_ashrrev_i32_e32 v2, 31, v0
	v_lshrrev_b32_e32 v2, 26, v2
	v_add_u32_e32 v2, v0, v2
	v_ashrrev_i32_e32 v153, 6, v2
	v_and_b32_e32 v2, 0xffc0, v2
	s_add_u32 s5, s90, 0x600000
	v_sub_u32_e32 v0, v0, v2
	s_addc_u32 s54, s91, 0
	v_lshrrev_b16_e32 v2, 7, v0
	s_add_i32 s4, s6, s4
	v_lshlrev_b32_e32 v1, 3, v152
	v_and_b32_e32 v2, 1, v2
	s_ashr_i32 s6, s4, 31
	v_and_b32_e32 v1, -16, v1
	v_add_u16_e32 v0, v0, v2
	s_lshr_b32 s6, s6, 27
	v_add_u32_e32 v1, v153, v1
	v_ashrrev_i16_sdwa v0, v3, sext(v0) dst_sel:DWORD dst_unused:UNUSED_PAD src0_sel:DWORD src1_sel:BYTE_0
	v_and_b32_e32 v3, 3, v153
	s_add_i32 s6, s4, s6
	v_and_or_b32 v3, v1, s7, v3
	s_ashr_i32 s7, s6, 5
	s_andn2_b32 s6, s6, 31
	s_sub_i32 s4, s4, s6
	s_bfe_i32 s6, s4, 0x80000
	s_bfe_u32 s6, s6, 0x3000c
	s_add_i32 s8, s4, s6
	s_bfe_i32 s6, s8, 0x80000
	s_and_b32 s8, s8, 0xf8
	s_sub_i32 s4, s4, s8
	v_lshlrev_b32_e32 v4, 5, v152
	v_bfe_i32 v154, v0, 0, 16
	v_lshlrev_b32_e32 v0, 1, v1
	v_lshrrev_b32_e32 v2, 2, v1
	s_lshl_b32 s7, s7, 3
	s_sext_i32_i8 s4, s4
	v_and_b32_e32 v4, 32, v4
	v_and_b32_e32 v0, 24, v0
	v_and_b32_e32 v2, 4, v2
	s_add_i32 s10, s7, s4
	v_or3_b32 v0, v3, v2, v0
	v_add_lshl_u32 v2, v4, v154, 1
	s_lshl_b32 s7, s10, 8
	v_lshl_add_u32 v132, v0, 11, v2
	v_and_b32_e32 v146, 15, v144
	v_ashrrev_i32_e32 v0, 1, v144
	s_sext_i32_i16 s9, s6
	s_add_i32 s7, s7, s72
	v_lshl_add_u32 v130, v1, 11, v2
	v_and_b32_e32 v0, -8, v0
	s_ashr_i32 s4, s9, 3
	v_or_b32_e32 v1, s7, v146
	v_readlane_b32 s8, v250, 32
	v_lshlrev_b32_e32 v1, 10, v1
	s_lshl_b32 s7, s4, 8
	v_add_u32_e32 v147, s8, v0
	v_add3_u32 v134, s7, v147, v1
	v_mov_b32_e32 v135, 0
	v_lshl_add_u64 v[0:1], v[134:135], 1, s[94:95]
	s_mov_b32 s7, 0x8000
	v_add_co_u32_e32 v2, vcc, s7, v0
	s_mov_b32 s7, 0x10000
	s_nop 0
	v_addc_co_u32_e32 v3, vcc, 0, v1, vcc
	global_load_dwordx4 v[60:63], v[0:1], off
	global_load_dwordx4 v[56:59], v[0:1], off offset:256
	global_load_dwordx4 v[52:55], v[2:3], off
	global_load_dwordx4 v[48:51], v[2:3], off offset:256
	v_add_co_u32_e32 v2, vcc, s7, v0
	s_mov_b32 s7, 0x18000
	s_nop 0
	v_addc_co_u32_e32 v3, vcc, 0, v1, vcc
	global_load_dwordx4 v[44:47], v[2:3], off
	global_load_dwordx4 v[40:43], v[2:3], off offset:256
	v_add_co_u32_e32 v2, vcc, s7, v0
	s_mov_b32 s7, 0x40000
	s_nop 0
	v_addc_co_u32_e32 v3, vcc, 0, v1, vcc
	global_load_dwordx4 v[36:39], v[2:3], off
	global_load_dwordx4 v[28:31], v[2:3], off offset:256
	v_add_co_u32_e32 v2, vcc, s7, v0
	s_mov_b32 s7, 0x48000
	s_nop 0
	v_addc_co_u32_e32 v3, vcc, 0, v1, vcc
	global_load_dwordx4 v[20:23], v[2:3], off
	global_load_dwordx4 v[8:11], v[2:3], off offset:256
	v_add_co_u32_e32 v2, vcc, s7, v0
	s_mov_b32 s7, 0x50000
	s_nop 0
	v_addc_co_u32_e32 v3, vcc, 0, v1, vcc
	s_ashr_i32 s11, s10, 31
	s_lshr_b32 s6, s9, 3
	global_load_dwordx4 v[12:15], v[2:3], off
	global_load_dwordx4 v[32:35], v[2:3], off offset:256
	v_add_co_u32_e32 v2, vcc, s7, v0
	s_lshl_b64 s[8:9], s[10:11], 19
	s_nop 0
	v_addc_co_u32_e32 v3, vcc, 0, v1, vcc
	s_mov_b32 s7, 0x58000
	s_add_u32 s22, s92, s8
	v_add_co_u32_e32 v0, vcc, s7, v0
	s_addc_u32 s23, s93, s9
	s_bfe_i64 s[6:7], s[6:7], 0x100000
	s_lshl_b64 s[6:7], s[6:7], 19
	s_add_u32 s24, s5, s6
	s_addc_u32 s25, s54, s7
	s_add_i32 s11, s0, 0
	v_addc_co_u32_e32 v1, vcc, 0, v1, vcc
	s_add_i32 m0, s11, 0x10000
	global_load_dwordx4 v[24:27], v[2:3], off
	global_load_dwordx4 v[16:19], v[2:3], off offset:256
	global_load_dwordx4 v[4:7], v[0:1], off
	s_nop 0
	global_load_dwordx4 v[0:3], v[0:1], off offset:256
	v_mov_b32_e32 v134, v64
	global_load_lds_dwordx4 v64, s[24:25]
	s_add_i32 m0, s11, 0x12000
	s_add_u32 s6, s24, 0x40000
	global_load_lds_dwordx4 v132, s[24:25]
	s_addc_u32 s7, s25, 0
	s_add_i32 m0, s11, 0x14000
	s_add_i32 s55, s11, 0x2000
	global_load_lds_dwordx4 v64, s[6:7]
	s_add_i32 m0, s11, 0x16000
	v_mov_b32_e32 v133, v135
	global_load_lds_dwordx4 v132, s[6:7]
	s_barrier
	s_mov_b32 m0, s11
	s_add_u32 s6, s22, 0x40000
	global_load_lds_dwordx4 v128, s[22:23]
	s_mov_b32 m0, s55
	s_addc_u32 s7, s23, 0
	s_add_i32 s56, s11, 0x4000
	global_load_lds_dwordx4 v130, s[22:23]
	s_mov_b32 m0, s56
	s_add_i32 s57, s11, 0x6000
	global_load_lds_dwordx4 v128, s[6:7]
	s_mov_b32 m0, s57
	v_mov_b32_e32 v129, v135
	global_load_lds_dwordx4 v130, s[6:7]
	v_mov_b32_e32 v131, v135
	s_mov_b32 s58, 0
	v_lshl_add_u64 v[142:143], s[24:25], 0, v[134:135]
	v_lshl_add_u64 v[140:141], s[24:25], 0, v[132:133]
	v_lshl_add_u64 v[138:139], s[22:23], 0, v[128:129]
	s_cmp_lg_u32 s1, 1
	v_lshl_add_u64 v[136:137], s[22:23], 0, v[130:131]
	s_cbranch_scc1 .LBB0_395
	s_barrier

; __device__ __forceinline__ void acc_from_xb(AccT& acc, const bf16_t* xb, const Unit& u, int wr, int wc, int fr, int fq) {
;     const unsigned off0 = (unsigned)(u.pm * BM + wr * 64 + fr) * DM + u.pn * BM + wc * 32 + 8 * fq;
; #pragma unroll
;     for (int ai = 0; ai < 2; ++ai)
; #pragma unroll
; template <class Epi, class Sched, bool ALIGN_EPI = false, bool SP2 = false>
; __device__ __forceinline__ void gemm_phase(PG8_LAS unsigned char* lds, const Gemm g, const Sched& S, const Epi& E, const int wid) {
;     const int lane = fresh_lane(), tid = wid * 64 + lane, wr = wid >> 2, wc = wid & 3, fr = lane & 15, fq = lane >> 4;
;     int nt = g.K / BK; asm volatile("" : "+s"(nt));
;     unsigned voffA[2], voffB[2];
; #pragma unroll
;     for (int i = 0; i < 2; ++i) { int R, C; stage_rc(tid * 16 + i * 8192, R, C); const int Rb = Epi::PERM ? ((R & ~31) + perm32(R & 31)) : R;
;         voffA[i] = (unsigned)(R * g.lda + C) * 2u; voffB[i] = (unsigned)(Rb * g.ldb + C) * 2u; }
;     const size_t kstep = (size_t)(BK * 2);
;     const size_t hstepA = (size_t)HALF * g.lda * 2, hstepB = (size_t)HALF * g.ldb * 2;
;     const size_t tstepA = 2 * hstepA, tstepB = 2 * hstepB;
;     const unsigned ldsw = (unsigned)wid * 1024u;
;     const int aoff = lds_byte(wr * 64 + fr, fq * 8), boff = lds_byte(wc * 32 + fr, fq * 8);
;     ...
;     Unit cur, nxt; int ui = 0;
;     if (!S.next(0, cur)) return;
;     f32x4 acc[2][2][4][2];
;     if constexpr (Epi::ACC_INIT) E.init(acc, cur, wr, wc, fr, fq);
;     else {
; #pragma unroll
;     for (int a = 0; a < 2; ++a)
; #pragma unroll
;         for (int b = 0; b < 2; ++b)
; #pragma unroll
;             for (int m = 0; m < 4; ++m)
; #pragma unroll
;                 for (int n = 0; n < 2; ++n) acc[a][b][m][n] = (f32x4){0.f, 0.f, 0.f, 0.f};
;     }
;     bf16x8 At[4][2], B0[2][2], B1[2][2];
;     const char* cA = cur.pn >= g.swap_pn ? (const char*)g.A2 + (size_t)(cur.pn - g.swap_pn) * tstepA : (const char*)g.A + (size_t)cur.pm * tstepA + (g.bd ? (size_t)(cur.pn >> 1) * 512 : 0);
;     const char* cB = cur.pn >= g.swap_pn ? (const char*)g.B2 + (size_t)cur.pm * tstepB : (const char*)g.Bt + (size_t)cur.pn * tstepB;
;     S.a_ready(cur);
;     if constexpr (SP2) {
;         PG8_STAGE(PG8_SB(0, 0), cB, voffB); PG8_STAGE(PG8_SB(0, 1), cB + hstepB, voffB); PG8_STAGE(PG8_SA(0, 0), cA, voffA); PG8_STAGE(PG8_SA(0, 1), cA + hstepA, voffA);
.Lrh_work_attn:
	v_lshlrev_b32_e32 v139, 4, v138
	v_add_u32_e32 v1, s0, v139
	v_add_u32_e32 v2, 0x2000, v1
	v_ashrrev_i32_e32 v3, 31, v2
	v_lshrrev_b32_e32 v3, 22, v3
	v_add_u32_e32 v3, v2, v3
	v_ashrrev_i32_e32 v136, 10, v3
	v_mul_i32_i24_e32 v3, 0x400, v136
	v_sub_u32_e32 v2, v2, v3
	v_lshrrev_b32_e32 v3, 4, v2
	v_bitop3_b32 v2, v3, v2, 32 bitop3:0x6c
	v_ashrrev_i32_e32 v3, 31, v2
	v_lshrrev_b32_e32 v3, 26, v3
	v_add_u32_e32 v3, v2, v3
	v_ashrrev_i32_e32 v137, 6, v3
	v_lshlrev_b32_e32 v4, 3, v136
	v_and_b32_e32 v3, 0xffc0, v3
	v_and_b32_e32 v4, -16, v4
	v_sub_u32_e32 v2, v2, v3
	v_add_u32_e32 v4, v137, v4
	v_lshrrev_b16_e32 v3, 7, v2
	v_and_b32_e32 v5, 3, v137
	s_mov_b32 s4, 0x1fffe0
	v_lshrrev_b32_e32 v6, 2, v4
	v_lshlrev_b32_e32 v7, 1, v4
	v_and_b32_e32 v3, 1, v3
	v_and_or_b32 v5, v4, s4, v5
	v_and_b32_e32 v6, 4, v6
	v_and_b32_e32 v7, 24, v7
	v_add_u16_e32 v2, v2, v3
	v_or3_b32 v5, v5, v6, v7
	v_lshlrev_b32_e32 v6, 5, v136
	v_ashrrev_i16_sdwa v2, v167, sext(v2) dst_sel:DWORD dst_unused:UNUSED_PAD src0_sel:DWORD src1_sel:BYTE_0
	v_and_b32_e32 v6, 32, v6
	v_bfe_i32 v143, v2, 0, 16
	v_add_lshl_u32 v2, v6, v143, 1
	v_lshl_add_u32 v128, v5, 11, v2
	v_lshl_add_u32 v130, v4, 11, v2
	v_ashrrev_i32_e32 v2, 31, v1
	v_lshrrev_b32_e32 v2, 22, v2
	v_add_u32_e32 v2, v1, v2
	v_ashrrev_i32_e32 v134, 10, v2
	v_mul_i32_i24_e32 v2, 0x400, v134
	v_sub_u32_e32 v1, v1, v2
	v_lshrrev_b32_e32 v2, 4, v1
	v_bitop3_b32 v1, v2, v1, 32 bitop3:0x6c
	v_ashrrev_i32_e32 v2, 31, v1
	v_lshrrev_b32_e32 v2, 26, v2
	v_add_u32_e32 v2, v1, v2
	v_lshlrev_b32_e32 v3, 3, v134
	v_ashrrev_i32_e32 v135, 6, v2
	v_and_b32_e32 v3, -16, v3
	v_add_u32_e32 v3, v135, v3
	v_and_b32_e32 v4, 3, v135
	v_lshrrev_b32_e32 v5, 2, v3
	v_lshlrev_b32_e32 v6, 1, v3
	v_and_b32_e32 v2, 0xc0, v2
	v_and_or_b32 v4, v3, s4, v4
	v_and_b32_e32 v5, 4, v5
	v_and_b32_e32 v6, 24, v6
	v_sub_u32_e32 v1, v1, v2
	v_or3_b32 v4, v4, v5, v6
	v_lshlrev_b32_e32 v5, 5, v134
	v_ashrrev_i16_sdwa v1, v167, sext(v1) dst_sel:DWORD dst_unused:UNUSED_PAD src0_sel:DWORD src1_sel:BYTE_0
	v_and_b32_e32 v5, 32, v5
	v_bfe_i32 v160, v1, 0, 16
	v_and_b32_e32 v140, 15, v138
	v_ashrrev_i32_e32 v0, 1, v138
	v_add_lshl_u32 v1, v5, v160, 1
	v_readlane_b32 s4, v249, 29
	v_and_b32_e32 v0, -8, v0
	v_lshl_add_u32 v146, v4, 11, v1
	v_lshl_add_u32 v132, v3, 11, v1
	v_or_b32_e32 v1, s4, v140
	v_readlane_b32 s4, v250, 32
	v_lshlrev_b32_e32 v1, 10, v1
	s_add_i32 s64, s0, 0
	v_add_u32_e32 v141, s4, v0
	v_readlane_b32 s4, v249, 30
	v_readlane_b32 s8, v249, 43
	s_add_i32 m0, s64, 0x10000
	v_add3_u32 v0, s4, v141, v1
	v_mov_b32_e32 v1, v147
	v_lshl_add_u64 v[0:1], v[0:1], 1, s[94:95]
	v_add_co_u32_e32 v2, vcc, s39, v0
	global_load_dwordx4 v[60:63], v[0:1], off
	global_load_dwordx4 v[56:59], v[0:1], off offset:256
	v_addc_co_u32_e32 v3, vcc, 0, v1, vcc
	global_load_dwordx4 v[52:55], v[2:3], off
	global_load_dwordx4 v[48:51], v[2:3], off offset:256
	v_add_co_u32_e32 v2, vcc, s52, v0
	s_mov_b32 s4, 0x40000
	s_nop 0
	v_addc_co_u32_e32 v3, vcc, 0, v1, vcc
	global_load_dwordx4 v[44:47], v[2:3], off
	global_load_dwordx4 v[40:43], v[2:3], off offset:256
	v_add_co_u32_e32 v2, vcc, s73, v0
	v_readlane_b32 s9, v249, 44
	s_nop 0
	v_addc_co_u32_e32 v3, vcc, 0, v1, vcc
	global_load_dwordx4 v[36:39], v[2:3], off
	global_load_dwordx4 v[20:23], v[2:3], off offset:256
	v_add_co_u32_e32 v2, vcc, s4, v0
	s_mov_b32 s4, 0x48000
	s_nop 0
	v_addc_co_u32_e32 v3, vcc, 0, v1, vcc
	global_load_dwordx4 v[16:19], v[2:3], off
	global_load_dwordx4 v[8:11], v[2:3], off offset:256
	v_add_co_u32_e32 v2, vcc, s4, v0
	s_mov_b32 s4, 0x50000
	s_nop 0
	v_addc_co_u32_e32 v3, vcc, 0, v1, vcc
	global_load_dwordx4 v[12:15], v[2:3], off
	global_load_dwordx4 v[32:35], v[2:3], off offset:256
	v_add_co_u32_e32 v2, vcc, s4, v0
	s_mov_b32 s4, 0x58000
	s_nop 0
	v_addc_co_u32_e32 v3, vcc, 0, v1, vcc
	v_add_co_u32_e32 v0, vcc, s4, v0
	global_load_dwordx4 v[28:31], v[2:3], off
	global_load_dwordx4 v[24:27], v[2:3], off offset:256
	v_addc_co_u32_e32 v1, vcc, 0, v1, vcc
	global_load_dwordx4 v[4:7], v[0:1], off
	s_nop 0
	global_load_dwordx4 v[0:3], v[0:1], off offset:256
	s_add_i32 s65, s64, 0x2000
	global_load_lds_dwordx4 v146, s[8:9]
	s_add_i32 m0, s64, 0x12000
	s_add_i32 s66, s64, 0x4000
	global_load_lds_dwordx4 v128, s[8:9]
	v_readlane_b32 s8, v249, 37
	s_add_i32 m0, s64, 0x14000
	v_readlane_b32 s9, v249, 38
	s_add_i32 s67, s64, 0x6000
	s_nop 3
	global_load_lds_dwordx4 v146, s[8:9]
	s_add_i32 m0, s64, 0x16000
	s_nop 0
	global_load_lds_dwordx4 v128, s[8:9]
	s_barrier
	v_readlane_b32 s8, v249, 39
	s_mov_b32 m0, s64
	v_readlane_b32 s9, v249, 40
	s_nop 4
	global_load_lds_dwordx4 v132, s[8:9]
	s_mov_b32 m0, s65
	s_nop 0
	global_load_lds_dwordx4 v130, s[8:9]
	v_readlane_b32 s8, v249, 41
	s_mov_b32 m0, s66
	v_readlane_b32 s9, v249, 42
	s_nop 4
	global_load_lds_dwordx4 v132, s[8:9]
	s_mov_b32 m0, s67
	s_nop 0
	global_load_lds_dwordx4 v130, s[8:9]
	v_readlane_b32 s8, v248, 1
	v_readlane_b32 s9, v248, 2
	s_andn2_b64 vcc, exec, s[8:9]
	s_cbranch_vccnz .LBB0_820
	s_barrier
